# grid syncs: one L1 invalidate per workgroup before the closing barrier instead of one per wave
# speedup vs baseline: 1.1641x; 1.0308x over previous
.Lsyncinv_6:
	buffer_inv sc1
	s_waitcnt vmcnt(0)
.LBB0_347:
	s_or_b64 exec, exec, s[0:1]
	v_readlane_b32 s0, v254, 4
	s_add_i32 s2, s0, 1
	v_readlane_b32 s0, v254, 0
	s_add_i32 s0, s0, 2
	v_readlane_b32 s1, v254, 5
	v_writelane_b32 v254, s0, 0
	s_nop 0
	v_readlane_b32 s0, v254, 2
	v_readlane_b32 s1, v254, 3
	s_add_u32 s0, s0, 0x2000
	s_addc_u32 s1, s1, 0
	s_add_u32 s80, s80, 0x100000
	s_addc_u32 s81, s81, 0
	s_add_u32 s82, s82, 0x100000
	s_addc_u32 s83, s83, 0
	s_barrier
	v_writelane_b32 v254, s0, 2
	s_add_u32 s86, s86, 0x100000
	s_waitcnt vmcnt(0) lgkmcnt(0)
	s_addc_u32 s87, s87, 0
	v_writelane_b32 v254, s1, 3
	s_mov_b32 s0, s2
	v_writelane_b32 v254, s0, 4
	s_cmp_eq_u32 s2, 4
	s_nop 0
	v_writelane_b32 v254, s1, 5
	s_cbranch_scc1 .LBB0_1524

; __global__ void __launch_bounds__(512, 2) hymba_fwd(Args A_unused) {
;     ...
;     unsigned nsync = 0;
.LBB0_812:
	s_or_b64 exec, exec, s[0:1]
	s_mov_b32 s0, s77
	s_barrier
	s_waitcnt vmcnt(0) lgkmcnt(0)
	v_mbcnt_lo_u32_b32 v0, -1, 0
	v_mbcnt_hi_u32_b32 v0, -1, v0
	s_mov_b32 s17, s67
	v_lshl_add_u32 v5, s0, 6, v0
	s_mov_b32 s18, s76
	v_readfirstlane_b32 s19, v5
	s_ashr_i32 s16, s19, 6
	v_and_b32_e32 v4, 63, v5
	s_mov_b64 s[0:1], s[68:69]
	s_load_dwordx2 s[2:3], s[0:1], 0xd8
	s_lshl_b32 s4, s18, 3
	s_add_i32 s4, s4, s16
	s_cmp_lt_u32 s4, 0x400
	s_mov_b32 s5, 0x29200000
	s_cselect_b32 s5, 0x2c000000, s5
	s_cselect_b64 s[6:7], -1, 0
	s_and_b32 s4, s4, 0x3ff
	s_lshl_b32 s4, s4, 12
	v_lshlrev_b32_e32 v228, 3, v4
	v_lshlrev_b32_e32 v229, 4, v4
	s_waitcnt lgkmcnt(0)
	s_add_u32 s2, s2, s5
	s_addc_u32 s3, s3, 0
	s_add_u32 s2, s2, s4
	s_addc_u32 s3, s3, 0
	s_and_b64 vcc, exec, s[6:7]
	s_cbranch_vccz .Lrel_v
	global_load_dwordx2 v[230:231], v228, s[2:3] offset:0
	global_load_dwordx2 v[232:233], v228, s[2:3] offset:512
	global_load_dwordx2 v[234:235], v228, s[2:3] offset:1024
	global_load_dwordx2 v[236:237], v228, s[2:3] offset:1536
	global_load_dwordx2 v[238:239], v228, s[2:3] offset:2048
	global_load_dwordx2 v[240:241], v228, s[2:3] offset:2560
	global_load_dwordx2 v[242:243], v228, s[2:3] offset:3072
	global_load_dwordx2 v[244:245], v228, s[2:3] offset:3584
	s_branch .Lrel_st

; __device__ __forceinline__ unsigned pk2(float lo, float hi) { return pg8::cvt_pk_bf16(lo, hi); }
; template <int PASS>
; __device__ __forceinline__ void s5_task(CArgs* Ap, int l, int b, int g, int c, LAS unsigned char* wl, int lane) {
;     ...
;     if (PASS == 2) {
;         float pr = ab_re, pi = ab_im;
; #pragma unroll
;         for (int i = 0; i < 9; ++i) { const float t_ = pr * pr - pi * pi; pi = 2.f * pr * pi; pr = t_; }
;         const f32x2* S = SST + (size_t)((b * NGRP + g) * NCHUNK) * NST + p;
;         for (int cc = 0; cc < c; ++cc) { const f32x2 s = S[(size_t)cc * NST]; const float t_ = pr * xr - pi * xi + s.x; xi = pr * xi + pi * xr + s.y; xr = t_; }
;         const float* cre = Ap->in[11] + ((size_t)(l * NGRP + g) * 16 + n16) * NST; const float* cim = Ap->in[12] + ((size_t)(l * NGRP + g) * 16 + n16) * NST;
; #pragma unroll
;         for (int kk = 0; kk < 4; ++kk) { const f32x4 r4 = *(const f32x4*)(cre + 16 * kk + 4 * g4), i4 = *(const f32x4*)(cim + 16 * kk + 4 * g4);
;             u32x4 w; w.x = pk2(r4[0], -i4[0]); w.y = pk2(r4[1], -i4[1]); w.z = pk2(r4[2], -i4[2]); w.w = pk2(r4[3], -i4[3]);
;             cB[kk] = __builtin_bit_cast(bf16x8, w); }
;         dval = Ap->in[13][l * DSSM + g * 16 + n16];
;     }
;     const size_t row0 = (size_t)b * SEQ + (size_t)c * CHUNK;
;     const bf16_t* up = P + (row0 + (lane >> 2)) * NINP + g * 16 + 4 * (lane & 3);
;     u32x2 unext = *(const u32x2*)up;
;     bf16_t* Y1 = (bf16_t*)(ws + WS_Y1);
.LBB0_866:
	v_writelane_b32 v254, s26, 15
	s_nop 1
	v_writelane_b32 v254, s27, 16
	s_or_b64 exec, exec, s[0:1]
	s_mov_b32 s0, s77
	s_barrier
	s_waitcnt vmcnt(0) lgkmcnt(0)
	v_mbcnt_lo_u32_b32 v0, -1, 0
	v_mbcnt_hi_u32_b32 v0, -1, v0
	s_mov_b32 s89, s67
	v_lshl_add_u32 v33, s0, 6, v0
	s_mov_b32 s91, s76
	v_readfirstlane_b32 s0, v33
	v_and_b32_e32 v89, 63, v33
	s_ashr_i32 s22, s0, 6
	s_mov_b64 s[2:3], s[68:69]
	s_cmpk_gt_i32 s91, 0xff
	v_lshlrev_b32_e32 v84, 4, v89
	v_and_b32_e32 v128, 15, v33
	v_and_b32_e32 v129, 48, v33
	v_lshlrev_b32_e32 v86, 3, v89
	s_cbranch_scc1 .LBB0_885
	s_load_dwordx2 s[28:29], s[2:3], 0xd8
	s_load_dwordx16 s[4:19], s[2:3], 0x30
	s_bfe_u32 s23, s0, 0x20006
	s_ashr_i32 s24, s0, 8
	s_lshl_b32 s0, s22, 13
	v_lshlrev_b32_e32 v1, 2, v89
	s_add_i32 s25, s0, 0
	v_lshrrev_b32_e32 v34, 2, v89
	v_and_b32_e32 v0, 12, v1
	s_waitcnt lgkmcnt(0)
	s_add_u32 s20, s28, 0x1ba00000
	v_readlane_b32 s0, v254, 4
	v_and_b32_e32 v35, 12, v34
	v_lshlrev_b32_e32 v2, 6, v34
	v_lshlrev_b32_e32 v3, 2, v0
	s_addc_u32 s21, s29, 0
	s_lshl_b32 s26, s0, 6
	v_lshlrev_b32_e32 v144, 2, v35
	v_lshl_or_b32 v85, s0, 10, v128
	v_add3_u32 v88, s25, v2, v3
	v_mov_b32_e32 v2, s25
	s_movk_i32 s0, 0x110
	v_readlane_b32 s1, v254, 5
	v_lshl_add_u64 v[36:37], s[14:15], 0, v[144:145]
	v_lshl_add_u64 v[38:39], s[16:17], 0, v[144:145]
	v_mad_u32_u24 v4, v128, s0, v2
	s_movk_i32 s0, 0xfef4
	v_lshlrev_b32_e32 v144, 1, v128
	v_mad_i32_i24 v5, v128, s0, v4
	v_lshl_add_u64 v[2:3], s[28:29], 0, v[144:145]
	s_mov_b64 s[0:1], 0x23200000
	v_lshl_add_u64 v[40:41], v[2:3], 0, s[0:1]
	v_or_b32_e32 v90, 1, v35
	v_or_b32_e32 v91, 2, v35
	v_or_b32_e32 v92, 3, v34
	s_add_u32 s0, s28, s80
	v_lshlrev_b32_e32 v2, 6, v35
	v_lshlrev_b32_e32 v3, 6, v90
	v_lshlrev_b32_e32 v6, 6, v91
	v_lshlrev_b32_e32 v7, 6, v92
	v_mov_b32_e32 v87, v145
	s_addc_u32 s1, s29, s81
	v_lshlrev_b32_e32 v32, 6, v128
	v_lshl_add_u64 v[42:43], s[0:1], 0, v[86:87]
	s_lshl_b32 s27, s23, 4
	s_lshl_b32 s28, s91, 2
	s_lshl_b32 s29, s89, 2
	v_or_b32_e32 v87, 0x400, v1
	v_lshlrev_b32_e32 v44, 1, v0
	v_add_u32_e32 v93, v4, v129
	v_add_u32_e32 v94, v5, v2
	v_add_u32_e32 v95, v5, v3
	v_add_u32_e32 v96, v5, v6
	v_add_u32_e32 v97, v5, v7
	s_mov_b32 s30, s91

;     __host__ __device__ bool next(int i, Unit& u) const {
;         const long L = (long)i * G + c; if (L >= nwg) return false;
;         int wgid = (int)L; { const int q = nwg / NXCD, r = nwg % NXCD, xcd = wgid % NXCD, off = wgid / NXCD; wgid = (xcd < r ? xcd * (q + 1) : r * (q + 1) + (xcd - r) * q) + off; }
;         const int nig = WGM * nN, gid = wgid / nig, fm = gid * WGM, gsz = (nM - fm) < WGM ? (nM - fm) : WGM;
;         u.pm = fm + ((wgid % nig) % gsz); u.pn = (wgid % nig) / gsz; return true;
; __global__ void __launch_bounds__(512, 2) hymba_fwd(Args A_unused) {
;     ...
;     unsigned nsync = 0;
.LBB0_1298:
	s_or_b64 exec, exec, s[0:1]
	s_barrier
	s_waitcnt vmcnt(0) lgkmcnt(0)
	s_mov_b32 s0, s77
	v_mbcnt_lo_u32_b32 v0, -1, 0
	v_mbcnt_hi_u32_b32 v0, -1, v0
	s_mov_b32 s28, s67
	v_lshl_add_u32 v8, s0, 6, v0
	s_mov_b32 s29, s76
	s_mov_b64 s[0:1], s[68:69]
	s_cmpk_gt_i32 s29, 0x1ff
	v_readfirstlane_b32 s11, v8
	s_cbranch_scc1 .LBB0_1322
	s_ashr_i32 s30, s29, 31
	s_lshr_b32 s2, s30, 29
	s_add_i32 s10, s29, s2
	s_and_b32 s2, s10, -8
	s_sub_i32 s9, s29, s2
	s_cmp_gt_i32 s9, -1
	s_mov_b64 s[4:5], -1
	s_cbranch_scc0 .LBB0_1301
	s_lshl_b32 s8, s9, 6
	s_mov_b64 s[4:5], 0

;     __host__ __device__ bool next(int i, Unit& u) const {
;         const long L = (long)i * G + c; if (L >= nwg) return false;
;         int wgid = (int)L; { const int q = nwg / NXCD, r = nwg % NXCD, xcd = wgid % NXCD, off = wgid / NXCD; wgid = (xcd < r ? xcd * (q + 1) : r * (q + 1) + (xcd - r) * q) + off; }
;         const int nig = WGM * nN, gid = wgid / nig, fm = gid * WGM, gsz = (nM - fm) < WGM ? (nM - fm) : WGM;
;         u.pm = fm + ((wgid % nig) % gsz); u.pn = (wgid % nig) / gsz; return true;
; __global__ void __launch_bounds__(512, 2) hymba_fwd(Args A_unused) {
;     ...
;     unsigned nsync = 0;
.LBB0_1336:
	s_or_b64 exec, exec, s[0:1]
	s_mov_b32 s0, s77
	s_barrier
	s_waitcnt vmcnt(0) lgkmcnt(0)
	v_mbcnt_lo_u32_b32 v0, -1, 0
	v_mbcnt_hi_u32_b32 v0, -1, v0
	s_mov_b32 s30, s76
	v_lshl_add_u32 v8, s0, 6, v0
	s_mov_b32 s31, s67
	s_mov_b64 s[0:1], s[68:69]
	s_load_dwordx2 s[2:3], s[0:1], 0xd8
	s_cmpk_lt_i32 s30, 0x200
	s_cselect_b64 s[4:5], -1, 0
	s_cmpk_gt_i32 s30, 0x1ff
	v_readfirstlane_b32 s10, v8
	s_cbranch_scc1 .LBB0_1342
	s_ashr_i32 s0, s30, 31
	s_lshr_b32 s0, s0, 29
	s_add_i32 s6, s30, s0
	s_and_b32 s0, s6, -8
	s_sub_i32 s7, s30, s0
	s_cmp_gt_i32 s7, -1
	s_mov_b64 s[0:1], -1
	s_cbranch_scc0 .LBB0_1339
	s_lshl_b32 s8, s7, 6
	s_mov_b64 s[0:1], 0

;     __host__ __device__ bool next(int i, Unit& u) const {
;         const long L = (long)i * G + c; if (L >= nwg) return false;
;         int wgid = (int)L; { const int q = nwg / NXCD, r = nwg % NXCD, xcd = wgid % NXCD, off = wgid / NXCD; wgid = (xcd < r ? xcd * (q + 1) : r * (q + 1) + (xcd - r) * q) + off; }
;         const int nig = WGM * nN, gid = wgid / nig, fm = gid * WGM, gsz = (nM - fm) < WGM ? (nM - fm) : WGM;
;         u.pm = fm + ((wgid % nig) % gsz); u.pn = (wgid % nig) / gsz; return true;
; __global__ void __launch_bounds__(512, 2) hymba_fwd(Args A_unused) {
;     ...
;     unsigned nsync = 0;
.LBB0_1392:
	s_or_b64 exec, exec, s[0:1]
	s_mov_b32 s0, s77
	s_barrier
	s_waitcnt vmcnt(0) lgkmcnt(0)
	v_mbcnt_lo_u32_b32 v0, -1, 0
	v_mbcnt_hi_u32_b32 v0, -1, v0
	s_mov_b32 s26, s67
	v_lshl_add_u32 v8, s0, 6, v0
	s_mov_b32 s27, s76
	s_mov_b64 s[0:1], s[68:69]
	s_load_dwordx2 s[8:9], s[0:1], 0xd8
	s_ashr_i32 s28, s27, 31
	s_cmpk_lt_i32 s27, 0xb00
	s_cselect_b64 s[0:1], -1, 0
	s_cmpk_gt_i32 s27, 0xaff
	s_mov_b32 s29, -1
	s_cbranch_scc1 .LBB0_1394
	s_lshr_b32 s2, s28, 29
	s_add_i32 s2, s27, s2
	s_ashr_i32 s3, s2, 3
	s_and_b32 s2, s2, -8
	s_sub_i32 s2, s27, s2
	s_cmp_lt_i32 s2, 0
	s_movk_i32 s4, 0x161
	s_cselect_b32 s4, s4, 0x160
	s_mul_i32 s2, s2, s4
	s_add_i32 s2, s2, s3
	s_mul_hi_i32 s3, s2, 0x2e8ba2e9
	s_lshr_b32 s4, s3, 31
	s_ashr_i32 s3, s3, 6
	s_add_i32 s3, s3, s4
	s_lshl_b32 s4, s3, 3
	s_mulk_i32 s3, 0x160
	s_sub_i32 s2, s2, s3
	s_bfe_u32 s3, s2, 0x3001c
	s_add_i32 s3, s2, s3
	s_and_b32 s3, s3, 0xfff8
	s_sub_i32 s2, s2, s3
	s_sext_i32_i16 s2, s2
	s_add_i32 s29, s4, s2

;     __device__ __forceinline__ float rs(int r, int fq) const { return (r >> 8) == tab_pm ? tab[r & 255] : row_rstd(rowsq, r, fq); }
; __device__ __forceinline__ float row_rstd(const float* part, int r, int fq) {
;     float s = 0.f;
; #pragma unroll
;     for (int k = 0; k < 8; ++k) s += part[(size_t)(fq * 8 + k) * MTOK + r];
;     s += __shfl_xor(s, 16); s += __shfl_xor(s, 32);
;     return rsqrtf(s * (1.f / DM) + EPS);
; }
;     __device__ __forceinline__ float rs(int r, int fq) const { return (r >> 8) == tab_pm ? tab[r & 255] : row_rstd(rowsq, r, fq); }
;     __device__ __forceinline__ void operator()(const f32x4 (&acc)[2][2][4][2], const pg8::Unit& u, int wr, int wc, int fr, int fq) const {
;         const int row0 = u.pm * 256 + wr * 64 + fr;
; #pragma unroll
;         for (int ai = 0; ai < 2; ++ai)
; #pragma unroll
;             for (int m = 0; m < 4; ++m) {
;                 const int r = row0 + ai * 128 + m * 16;
;                 const float rstd = rs(r, fq);
.LBB0_1414:
	s_lshl_b32 s1, s4, 8
	s_add_i32 s1, s1, s41
	v_or_b32_e32 v138, s1, v141
	s_ashr_i32 s1, s1, 8
	s_cmp_lg_u32 s1, s29
	s_cselect_b64 s[20:21], -1, 0
	s_mov_b64 s[4:5], -1
	s_and_b64 vcc, exec, s[20:21]
	v_ashrrev_i32_e32 v139, 31, v138
	s_cbranch_vccz .LBB0_1416
	v_lshl_add_u64 v[136:137], v[138:139], 2, v[130:131]
	v_add_co_u32_e32 v150, vcc, 0x10000, v136
	s_mov_b64 s[4:5], 0
	s_nop 0
	v_addc_co_u32_e32 v151, vcc, 0, v137, vcc
	v_add_co_u32_e32 v154, vcc, 0x20000, v136
	s_nop 1
	v_addc_co_u32_e32 v155, vcc, 0, v137, vcc
	v_add_co_u32_e32 v156, vcc, 0x30000, v136
	s_nop 1
	v_addc_co_u32_e32 v157, vcc, 0, v137, vcc
	v_add_co_u32_e32 v158, vcc, 0x40000, v136
	s_nop 1
	v_addc_co_u32_e32 v159, vcc, 0, v137, vcc
	v_add_co_u32_e32 v160, vcc, 0x50000, v136
	s_nop 1
	v_addc_co_u32_e32 v161, vcc, 0, v137, vcc
	v_add_co_u32_e32 v162, vcc, 0x60000, v136
	s_nop 1
	v_addc_co_u32_e32 v163, vcc, 0, v137, vcc
	v_add_co_u32_e32 v164, vcc, 0x70000, v136
	s_nop 1
	v_addc_co_u32_e32 v165, vcc, 0, v137, vcc
	v_mov_b32_e32 v194, v136
	v_mov_b32_e32 v195, v137
	v_mov_b32_e32 v196, v150
	v_mov_b32_e32 v197, v151
	v_mov_b32_e32 v198, v154
	v_mov_b32_e32 v199, v155
	v_mov_b32_e32 v200, v156
	v_mov_b32_e32 v201, v157
	v_mov_b32_e32 v202, v158
	v_mov_b32_e32 v203, v159
	v_mov_b32_e32 v204, v160
	v_mov_b32_e32 v205, v161
	v_mov_b32_e32 v206, v162
	v_mov_b32_e32 v207, v163
	v_mov_b32_e32 v208, v164
	v_mov_b32_e32 v209, v165
	global_load_dword v228, v[194:195], off
	global_load_dword v229, v[196:197], off
	global_load_dword v230, v[198:199], off
	global_load_dword v231, v[200:201], off
	global_load_dword v232, v[202:203], off
	global_load_dword v233, v[204:205], off
	global_load_dword v234, v[206:207], off
	global_load_dword v235, v[208:209], off
	global_load_dword v236, v[194:195], off offset:64
	global_load_dword v237, v[196:197], off offset:64
	global_load_dword v238, v[198:199], off offset:64
	global_load_dword v239, v[200:201], off offset:64
	global_load_dword v240, v[202:203], off offset:64
	global_load_dword v241, v[204:205], off offset:64
	global_load_dword v242, v[206:207], off offset:64
	global_load_dword v243, v[208:209], off offset:64
	global_load_dword v244, v[194:195], off offset:128
	global_load_dword v245, v[196:197], off offset:128
	global_load_dword v246, v[198:199], off offset:128
	global_load_dword v247, v[200:201], off offset:128
	global_load_dword v248, v[202:203], off offset:128
	global_load_dword v249, v[204:205], off offset:128
	global_load_dword v250, v[206:207], off offset:128
	global_load_dword v251, v[208:209], off offset:128
	global_load_dword v252, v[194:195], off offset:192
	global_load_dword v253, v[196:197], off offset:192
	global_load_dword v188, v[198:199], off offset:192
	global_load_dword v189, v[200:201], off offset:192
	global_load_dword v190, v[202:203], off offset:192
	global_load_dword v191, v[204:205], off offset:192
	global_load_dword v192, v[206:207], off offset:192
	global_load_dword v193, v[208:209], off offset:192
	v_xor_b32_e32 v156, 16, v170
	v_cmp_lt_i32_e32 vcc, v156, v171
	s_waitcnt vmcnt(24)
	v_mov_b32_e32 v136, v228
	v_mov_b32_e32 v137, v229
	v_mov_b32_e32 v140, v230
	v_mov_b32_e32 v150, v231
	v_mov_b32_e32 v151, v232
	v_mov_b32_e32 v153, v233
	v_mov_b32_e32 v154, v234
	v_mov_b32_e32 v155, v235
	global_load_dword v228, v[194:195], off offset:512
	global_load_dword v229, v[196:197], off offset:512
	global_load_dword v230, v[198:199], off offset:512
	global_load_dword v231, v[200:201], off offset:512
	global_load_dword v232, v[202:203], off offset:512
	global_load_dword v233, v[204:205], off offset:512
	global_load_dword v234, v[206:207], off offset:512
	global_load_dword v235, v[208:209], off offset:512
	v_add_f32_e32 v136, 0, v136
	v_add_f32_e32 v136, v136, v137
	v_add_f32_e32 v136, v136, v140
	v_add_f32_e32 v136, v136, v150
	v_add_f32_e32 v136, v136, v151
	v_add_f32_e32 v136, v136, v153
	v_cndmask_b32_e32 v156, v170, v156, vcc
	v_add_f32_e32 v136, v136, v154
	v_lshlrev_b32_e32 v156, 2, v156
	v_add_f32_e32 v136, v136, v155
	ds_bpermute_b32 v137, v156, v136
	v_xor_b32_e32 v140, 32, v170
	v_cmp_lt_i32_e32 vcc, v140, v171
	s_waitcnt lgkmcnt(0)
	v_add_f32_e32 v136, v136, v137
	v_cndmask_b32_e32 v140, v170, v140, vcc
	v_lshlrev_b32_e32 v140, 2, v140
	ds_bpermute_b32 v137, v140, v136
	s_waitcnt lgkmcnt(0)
	v_add_f32_e32 v136, v136, v137
	v_fmamk_f32 v136, v136, 0x3a000000, v167
	v_mul_f32_e32 v137, 0x4b800000, v136
	v_cmp_gt_f32_e32 vcc, s33, v136
	s_nop 1
	v_cndmask_b32_e32 v136, v136, v137, vcc
	v_rsq_f32_e32 v136, v136
	s_nop 0
	v_mul_f32_e32 v137, 0x45800000, v136
	v_cndmask_b32_e32 v140, v136, v137, vcc

; __device__ __forceinline__ unsigned pk2(float lo, float hi) { return pg8::cvt_pk_bf16(lo, hi); }
; __device__ __forceinline__ float sigmoidf_(float x) { return __builtin_amdgcn_rcpf(1.f + fexp(-x)); }
; __device__ __forceinline__ float row_rstd(const float* part, int r, int fq) {
;     float s = 0.f;
; #pragma unroll
;     for (int k = 0; k < 8; ++k) s += part[(size_t)(fq * 8 + k) * MTOK + r];
;     s += __shfl_xor(s, 16); s += __shfl_xor(s, 32);
;     return rsqrtf(s * (1.f / DM) + EPS);
; }
;     __device__ __forceinline__ void operator()(const f32x4 (&acc)[2][2][4][2], const pg8::Unit& u, int wr, int wc, int fr, int fq) const {
;     ...
;                 float o[2][4];
; #pragma unroll
;                 for (int bj = 0; bj < 2; ++bj) {
;                     const f32x4 gv = acc[ai][bj][m][0] * rstd, uv = acc[ai][bj][m][1] * rstd;
; #pragma unroll
;                     for (int i = 0; i < 4; ++i) o[bj][i] = gv[i] * sigmoidf_(gv[i]) * uv[i];
;                 }
;                 const int j0 = u.pn * 128 + wc * 32 + 8 * fq;
;                 u32x4 w; w.x = pk2(o[0][0], o[0][1]); w.y = pk2(o[0][2], o[0][3]); w.z = pk2(o[1][0], o[1][1]); w.w = pk2(o[1][2], o[1][3]);
;                 *(u32x4*)(HID + (size_t)r * DFF + j0) = w;
.LBB0_1418:
	s_waitcnt lgkmcnt(0)
	v_pk_mul_f32 v[124:125], v[124:125], v[140:141] op_sel_hi:[1,0]
	v_pk_mul_f32 v[126:127], v[126:127], v[140:141] op_sel_hi:[1,0]
	v_mul_f32_e32 v137, 0xbfb8aa3b, v124
	v_exp_f32_e32 v150, v137
	v_mul_f32_e32 v137, 0xbfb8aa3b, v125
	v_mul_f32_e32 v153, 0xbfb8aa3b, v126
	v_exp_f32_e32 v151, v137
	v_exp_f32_e32 v153, v153
	v_mul_f32_e32 v154, 0xbfb8aa3b, v127
	v_exp_f32_e32 v155, v154
	v_add_f32_e32 v150, 1.0, v150
	v_add_f32_e32 v151, 1.0, v151
	v_add_f32_e32 v153, 1.0, v153
	v_rcp_f32_e32 v150, v150
	v_rcp_f32_e32 v151, v151
	v_rcp_f32_e32 v154, v153
	v_add_f32_e32 v153, 1.0, v155
	v_rcp_f32_e32 v155, v153
	v_pk_mul_f32 v[124:125], v[124:125], v[150:151]
	v_pk_mul_f32 v[120:121], v[120:121], v[140:141] op_sel_hi:[1,0]
	v_pk_mul_f32 v[116:117], v[116:117], v[140:141] op_sel_hi:[1,0]
	v_pk_mul_f32 v[120:121], v[120:121], v[124:125]
	v_pk_mul_f32 v[124:125], v[126:127], v[154:155]
	v_mul_f32_e32 v126, 0xbfb8aa3b, v116
	v_mul_f32_e32 v127, 0xbfb8aa3b, v117
	v_exp_f32_e32 v126, v126
	v_exp_f32_e32 v127, v127
	v_pk_mul_f32 v[122:123], v[122:123], v[140:141] op_sel_hi:[1,0]
	v_pk_mul_f32 v[118:119], v[118:119], v[140:141] op_sel_hi:[1,0]
	v_pk_mul_f32 v[122:123], v[122:123], v[124:125]
	v_add_f32_e32 v124, 1.0, v126
	v_add_f32_e32 v125, 1.0, v127
	v_mul_f32_e32 v126, 0xbfb8aa3b, v118
	v_mul_f32_e32 v127, 0xbfb8aa3b, v119
	v_exp_f32_e32 v126, v126
	v_exp_f32_e32 v127, v127
	v_rcp_f32_e32 v124, v124
	v_rcp_f32_e32 v125, v125
	v_add_f32_e32 v126, 1.0, v126
	v_add_f32_e32 v127, 1.0, v127
	v_rcp_f32_e32 v126, v126
	v_rcp_f32_e32 v127, v127
	v_pk_mul_f32 v[116:117], v[116:117], v[124:125]
	v_pk_mul_f32 v[112:113], v[112:113], v[140:141] op_sel_hi:[1,0]
	v_pk_mul_f32 v[114:115], v[114:115], v[140:141] op_sel_hi:[1,0]
	v_pk_mul_f32 v[116:117], v[112:113], v[116:117]
	v_pk_mul_f32 v[112:113], v[118:119], v[126:127]
	v_lshl_or_b32 v136, s0, 7, v143
	v_pk_mul_f32 v[118:119], v[114:115], v[112:113]
	v_cvt_pk_bf16_f32 v114, v116, v117
	v_mov_b64_e32 v[116:117], s[8:9]
	v_mad_u64_u32 v[116:117], s[0:1], v138, s90, v[116:117]
	v_cvt_pk_bf16_f32 v115, v118, v119
	v_mov_b32_e32 v118, v117
	v_mad_u64_u32 v[118:119], s[0:1], v139, s90, v[118:119]
	v_ashrrev_i32_e32 v137, 31, v136
	v_mov_b32_e32 v117, v118
	v_cvt_pk_bf16_f32 v112, v120, v121
	v_cvt_pk_bf16_f32 v113, v122, v123
	v_lshl_add_u64 v[116:117], v[136:137], 1, v[116:117]
	global_store_dwordx4 v[116:117], v[112:115], off
	s_mov_b64 s[0:1], -1
	s_andn2_b64 vcc, exec, s[20:21]
	v_or_b32_e32 v112, 16, v138
	v_cndmask_b32_e64 v113, 0, 1, s[20:21]
	v_cmp_ne_u32_e64 s[4:5], 1, v113
	v_ashrrev_i32_e32 v113, 31, v112
	s_cbranch_vccnz .LBB0_1420
	v_lshl_add_u64 v[114:115], v[138:139], 2, v[130:131]
	v_add_co_u32_e32 v116, vcc, 0x10000, v114
	s_mov_b64 s[0:1], 0
	s_nop 0
	v_addc_co_u32_e32 v117, vcc, 0, v115, vcc
	v_add_co_u32_e32 v118, vcc, 0x20000, v114
	s_nop 1
	v_addc_co_u32_e32 v119, vcc, 0, v115, vcc
	v_add_co_u32_e32 v120, vcc, 0x30000, v114
	s_nop 1
	v_addc_co_u32_e32 v121, vcc, 0, v115, vcc
	v_add_co_u32_e32 v122, vcc, 0x40000, v114
	s_nop 1
	v_addc_co_u32_e32 v123, vcc, 0, v115, vcc
	v_add_co_u32_e32 v124, vcc, 0x50000, v114
	s_nop 1
	v_addc_co_u32_e32 v125, vcc, 0, v115, vcc
	v_add_co_u32_e32 v126, vcc, 0x60000, v114
	s_nop 1
	v_addc_co_u32_e32 v127, vcc, 0, v115, vcc
	v_add_co_u32_e32 v150, vcc, 0x70000, v114
	s_nop 1
	v_addc_co_u32_e32 v151, vcc, 0, v115, vcc
	v_xor_b32_e32 v122, 16, v170
	v_cmp_lt_i32_e32 vcc, v122, v171
	s_waitcnt vmcnt(25)
	v_mov_b32_e32 v114, v236
	v_mov_b32_e32 v115, v237
	v_mov_b32_e32 v116, v238
	v_mov_b32_e32 v117, v239
	v_mov_b32_e32 v118, v240
	v_mov_b32_e32 v119, v241
	v_mov_b32_e32 v120, v242
	v_mov_b32_e32 v121, v243
	global_load_dword v236, v[194:195], off offset:576
	global_load_dword v237, v[196:197], off offset:576
	global_load_dword v238, v[198:199], off offset:576
	global_load_dword v239, v[200:201], off offset:576
	global_load_dword v240, v[202:203], off offset:576
	global_load_dword v241, v[204:205], off offset:576
	global_load_dword v242, v[206:207], off offset:576
	global_load_dword v243, v[208:209], off offset:576
	v_add_f32_e32 v114, 0, v114
	v_add_f32_e32 v114, v114, v115
	v_add_f32_e32 v114, v114, v116
	v_add_f32_e32 v114, v114, v117
	v_add_f32_e32 v114, v114, v118
	v_add_f32_e32 v114, v114, v119
	v_cndmask_b32_e32 v122, v170, v122, vcc
	v_add_f32_e32 v114, v114, v120
	v_lshlrev_b32_e32 v122, 2, v122
	v_add_f32_e32 v114, v114, v121
	ds_bpermute_b32 v115, v122, v114
	v_xor_b32_e32 v116, 32, v170
	v_cmp_lt_i32_e32 vcc, v116, v171
	s_waitcnt lgkmcnt(0)
	v_add_f32_e32 v114, v114, v115
	v_cndmask_b32_e32 v116, v170, v116, vcc
	v_lshlrev_b32_e32 v116, 2, v116
	ds_bpermute_b32 v115, v116, v114
	s_waitcnt lgkmcnt(0)
	v_add_f32_e32 v114, v114, v115
	v_fmamk_f32 v114, v114, 0x3a000000, v167
	v_mul_f32_e32 v115, 0x4b800000, v114
	v_cmp_gt_f32_e32 vcc, s33, v114
	s_nop 1
	v_cndmask_b32_e32 v114, v114, v115, vcc
	v_rsq_f32_e32 v114, v114
	s_nop 0
	v_mul_f32_e32 v115, 0x45800000, v114
	v_cndmask_b32_e32 v114, v114, v115, vcc

; __device__ __forceinline__ unsigned pk2(float lo, float hi) { return pg8::cvt_pk_bf16(lo, hi); }
; __device__ __forceinline__ float sigmoidf_(float x) { return __builtin_amdgcn_rcpf(1.f + fexp(-x)); }
; __device__ __forceinline__ float row_rstd(const float* part, int r, int fq) {
;     float s = 0.f;
; #pragma unroll
;     for (int k = 0; k < 8; ++k) s += part[(size_t)(fq * 8 + k) * MTOK + r];
;     s += __shfl_xor(s, 16); s += __shfl_xor(s, 32);
;     return rsqrtf(s * (1.f / DM) + EPS);
; }
;     __device__ __forceinline__ void operator()(const f32x4 (&acc)[2][2][4][2], const pg8::Unit& u, int wr, int wc, int fr, int fq) const {
;     ...
;                 float o[2][4];
; #pragma unroll
;                 for (int bj = 0; bj < 2; ++bj) {
;                     const f32x4 gv = acc[ai][bj][m][0] * rstd, uv = acc[ai][bj][m][1] * rstd;
; #pragma unroll
;                     for (int i = 0; i < 4; ++i) o[bj][i] = gv[i] * sigmoidf_(gv[i]) * uv[i];
;                 }
;                 const int j0 = u.pn * 128 + wc * 32 + 8 * fq;
;                 u32x4 w; w.x = pk2(o[0][0], o[0][1]); w.y = pk2(o[0][2], o[0][3]); w.z = pk2(o[1][0], o[1][1]); w.w = pk2(o[1][2], o[1][3]);
;                 *(u32x4*)(HID + (size_t)r * DFF + j0) = w;
.LBB0_1422:
	s_waitcnt lgkmcnt(0)
	v_pk_mul_f32 v[108:109], v[108:109], v[114:115] op_sel_hi:[1,0]
	s_and_b64 vcc, exec, s[4:5]
	v_mul_f32_e32 v115, 0xbfb8aa3b, v108
	v_exp_f32_e32 v115, v115
	v_mul_f32_e32 v116, 0xbfb8aa3b, v109
	v_exp_f32_e32 v116, v116
	v_add_f32_e32 v115, 1.0, v115
	v_pk_mul_f32 v[110:111], v[110:111], v[114:115] op_sel_hi:[1,0]
	v_add_f32_e32 v117, 1.0, v116
	v_rcp_f32_e32 v116, v115
	v_mul_f32_e32 v115, 0xbfb8aa3b, v110
	v_exp_f32_e32 v115, v115
	v_mul_f32_e32 v118, 0xbfb8aa3b, v111
	v_exp_f32_e32 v119, v118
	v_rcp_f32_e32 v117, v117
	v_add_f32_e32 v115, 1.0, v115
	v_rcp_f32_e32 v118, v115
	v_add_f32_e32 v115, 1.0, v119
	v_rcp_f32_e32 v119, v115
	v_pk_mul_f32 v[108:109], v[108:109], v[116:117]
	v_pk_mul_f32 v[104:105], v[104:105], v[114:115] op_sel_hi:[1,0]
	v_pk_mul_f32 v[100:101], v[100:101], v[114:115] op_sel_hi:[1,0]
	v_pk_mul_f32 v[104:105], v[104:105], v[108:109]
	v_pk_mul_f32 v[108:109], v[110:111], v[118:119]
	v_mul_f32_e32 v110, 0xbfb8aa3b, v100
	v_mul_f32_e32 v111, 0xbfb8aa3b, v101
	v_exp_f32_e32 v110, v110
	v_exp_f32_e32 v111, v111
	v_pk_mul_f32 v[106:107], v[106:107], v[114:115] op_sel_hi:[1,0]
	v_pk_mul_f32 v[102:103], v[102:103], v[114:115] op_sel_hi:[1,0]
	v_pk_mul_f32 v[106:107], v[106:107], v[108:109]
	v_add_f32_e32 v108, 1.0, v110
	v_add_f32_e32 v109, 1.0, v111
	v_mul_f32_e32 v110, 0xbfb8aa3b, v102
	v_mul_f32_e32 v111, 0xbfb8aa3b, v103
	v_exp_f32_e32 v110, v110
	v_exp_f32_e32 v111, v111
	v_rcp_f32_e32 v108, v108
	v_rcp_f32_e32 v109, v109
	v_add_f32_e32 v110, 1.0, v110
	v_add_f32_e32 v111, 1.0, v111
	v_rcp_f32_e32 v110, v110
	v_rcp_f32_e32 v111, v111
	v_pk_mul_f32 v[100:101], v[100:101], v[108:109]
	v_pk_mul_f32 v[96:97], v[96:97], v[114:115] op_sel_hi:[1,0]
	v_pk_mul_f32 v[98:99], v[98:99], v[114:115] op_sel_hi:[1,0]
	v_pk_mul_f32 v[100:101], v[96:97], v[100:101]
	v_pk_mul_f32 v[96:97], v[102:103], v[110:111]
	s_nop 0
	v_pk_mul_f32 v[102:103], v[98:99], v[96:97]
	v_cvt_pk_bf16_f32 v98, v100, v101
	v_mov_b64_e32 v[100:101], s[8:9]
	v_mad_u64_u32 v[100:101], s[0:1], v112, s90, v[100:101]
	v_cvt_pk_bf16_f32 v99, v102, v103
	v_mov_b32_e32 v102, v101
	v_mad_u64_u32 v[102:103], s[0:1], v113, s90, v[102:103]
	v_mov_b32_e32 v101, v102
	v_cvt_pk_bf16_f32 v96, v104, v105
	v_cvt_pk_bf16_f32 v97, v106, v107
	v_lshl_add_u64 v[100:101], v[136:137], 1, v[100:101]
	global_store_dwordx4 v[100:101], v[96:99], off
	s_mov_b64 s[0:1], -1
	s_nop 0
	v_or_b32_e32 v96, 32, v138
	v_ashrrev_i32_e32 v97, 31, v96
	s_cbranch_vccnz .LBB0_1424
	v_lshl_add_u64 v[98:99], v[138:139], 2, v[130:131]
	v_add_co_u32_e32 v100, vcc, 0x10000, v98
	s_mov_b64 s[0:1], 0
	s_nop 0
	v_addc_co_u32_e32 v101, vcc, 0, v99, vcc
	v_add_co_u32_e32 v102, vcc, 0x20000, v98
	s_nop 1
	v_addc_co_u32_e32 v103, vcc, 0, v99, vcc
	v_add_co_u32_e32 v104, vcc, 0x30000, v98
	s_nop 1
	v_addc_co_u32_e32 v105, vcc, 0, v99, vcc
	v_add_co_u32_e32 v106, vcc, 0x40000, v98
	s_nop 1
	v_addc_co_u32_e32 v107, vcc, 0, v99, vcc
	v_add_co_u32_e32 v108, vcc, 0x50000, v98
	s_nop 1
	v_addc_co_u32_e32 v109, vcc, 0, v99, vcc
	v_add_co_u32_e32 v110, vcc, 0x60000, v98
	s_nop 1
	v_addc_co_u32_e32 v111, vcc, 0, v99, vcc
	v_add_co_u32_e32 v112, vcc, 0x70000, v98
	s_nop 1
	v_addc_co_u32_e32 v113, vcc, 0, v99, vcc
	v_xor_b32_e32 v106, 16, v170
	v_cmp_lt_i32_e32 vcc, v106, v171
	s_waitcnt vmcnt(26)
	v_mov_b32_e32 v98, v244
	v_mov_b32_e32 v99, v245
	v_mov_b32_e32 v100, v246
	v_mov_b32_e32 v101, v247
	v_mov_b32_e32 v102, v248
	v_mov_b32_e32 v103, v249
	v_mov_b32_e32 v104, v250
	v_mov_b32_e32 v105, v251
	global_load_dword v244, v[194:195], off offset:640
	global_load_dword v245, v[196:197], off offset:640
	global_load_dword v246, v[198:199], off offset:640
	global_load_dword v247, v[200:201], off offset:640
	global_load_dword v248, v[202:203], off offset:640
	global_load_dword v249, v[204:205], off offset:640
	global_load_dword v250, v[206:207], off offset:640
	global_load_dword v251, v[208:209], off offset:640
	v_add_f32_e32 v98, 0, v98
	v_add_f32_e32 v98, v98, v99
	v_add_f32_e32 v98, v98, v100
	v_add_f32_e32 v98, v98, v101
	v_add_f32_e32 v98, v98, v102
	v_add_f32_e32 v98, v98, v103
	v_cndmask_b32_e32 v106, v170, v106, vcc
	v_add_f32_e32 v98, v98, v104
	v_lshlrev_b32_e32 v106, 2, v106
	v_add_f32_e32 v98, v98, v105
	ds_bpermute_b32 v99, v106, v98
	v_xor_b32_e32 v100, 32, v170
	v_cmp_lt_i32_e32 vcc, v100, v171
	s_waitcnt lgkmcnt(0)
	v_add_f32_e32 v98, v98, v99
	v_cndmask_b32_e32 v100, v170, v100, vcc
	v_lshlrev_b32_e32 v100, 2, v100
	ds_bpermute_b32 v99, v100, v98
	s_waitcnt lgkmcnt(0)
	v_add_f32_e32 v98, v98, v99
	v_fmamk_f32 v98, v98, 0x3a000000, v167
	v_mul_f32_e32 v99, 0x4b800000, v98
	v_cmp_gt_f32_e32 vcc, s33, v98
	s_nop 1
	v_cndmask_b32_e32 v98, v98, v99, vcc
	v_rsq_f32_e32 v98, v98
	s_nop 0
	v_mul_f32_e32 v99, 0x45800000, v98
	v_cndmask_b32_e32 v98, v98, v99, vcc

; __device__ __forceinline__ unsigned pk2(float lo, float hi) { return pg8::cvt_pk_bf16(lo, hi); }
; __device__ __forceinline__ float sigmoidf_(float x) { return __builtin_amdgcn_rcpf(1.f + fexp(-x)); }
; __device__ __forceinline__ float row_rstd(const float* part, int r, int fq) {
;     float s = 0.f;
; #pragma unroll
;     for (int k = 0; k < 8; ++k) s += part[(size_t)(fq * 8 + k) * MTOK + r];
;     s += __shfl_xor(s, 16); s += __shfl_xor(s, 32);
;     return rsqrtf(s * (1.f / DM) + EPS);
; }
;     __device__ __forceinline__ void operator()(const f32x4 (&acc)[2][2][4][2], const pg8::Unit& u, int wr, int wc, int fr, int fq) const {
;     ...
;                 float o[2][4];
; #pragma unroll
;                 for (int bj = 0; bj < 2; ++bj) {
;                     const f32x4 gv = acc[ai][bj][m][0] * rstd, uv = acc[ai][bj][m][1] * rstd;
; #pragma unroll
;                     for (int i = 0; i < 4; ++i) o[bj][i] = gv[i] * sigmoidf_(gv[i]) * uv[i];
;                 }
;                 const int j0 = u.pn * 128 + wc * 32 + 8 * fq;
;                 u32x4 w; w.x = pk2(o[0][0], o[0][1]); w.y = pk2(o[0][2], o[0][3]); w.z = pk2(o[1][0], o[1][1]); w.w = pk2(o[1][2], o[1][3]);
;                 *(u32x4*)(HID + (size_t)r * DFF + j0) = w;
.LBB0_1426:
	s_waitcnt lgkmcnt(0)
	v_pk_mul_f32 v[92:93], v[92:93], v[98:99] op_sel_hi:[1,0]
	s_and_b64 vcc, exec, s[4:5]
	v_mul_f32_e32 v99, 0xbfb8aa3b, v92
	v_exp_f32_e32 v99, v99
	v_mul_f32_e32 v100, 0xbfb8aa3b, v93
	v_exp_f32_e32 v100, v100
	v_add_f32_e32 v99, 1.0, v99
	v_pk_mul_f32 v[94:95], v[94:95], v[98:99] op_sel_hi:[1,0]
	v_add_f32_e32 v101, 1.0, v100
	v_rcp_f32_e32 v100, v99
	v_mul_f32_e32 v99, 0xbfb8aa3b, v94
	v_exp_f32_e32 v99, v99
	v_mul_f32_e32 v102, 0xbfb8aa3b, v95
	v_exp_f32_e32 v103, v102
	v_rcp_f32_e32 v101, v101
	v_add_f32_e32 v99, 1.0, v99
	v_rcp_f32_e32 v102, v99
	v_add_f32_e32 v99, 1.0, v103
	v_rcp_f32_e32 v103, v99
	v_pk_mul_f32 v[92:93], v[92:93], v[100:101]
	v_pk_mul_f32 v[88:89], v[88:89], v[98:99] op_sel_hi:[1,0]
	v_pk_mul_f32 v[84:85], v[84:85], v[98:99] op_sel_hi:[1,0]
	v_pk_mul_f32 v[88:89], v[88:89], v[92:93]
	v_pk_mul_f32 v[92:93], v[94:95], v[102:103]
	v_mul_f32_e32 v94, 0xbfb8aa3b, v84
	v_mul_f32_e32 v95, 0xbfb8aa3b, v85
	v_exp_f32_e32 v94, v94
	v_exp_f32_e32 v95, v95
	v_pk_mul_f32 v[90:91], v[90:91], v[98:99] op_sel_hi:[1,0]
	v_pk_mul_f32 v[86:87], v[86:87], v[98:99] op_sel_hi:[1,0]
	v_pk_mul_f32 v[90:91], v[90:91], v[92:93]
	v_add_f32_e32 v92, 1.0, v94
	v_add_f32_e32 v93, 1.0, v95
	v_mul_f32_e32 v94, 0xbfb8aa3b, v86
	v_mul_f32_e32 v95, 0xbfb8aa3b, v87
	v_exp_f32_e32 v94, v94
	v_exp_f32_e32 v95, v95
	v_rcp_f32_e32 v92, v92
	v_rcp_f32_e32 v93, v93
	v_add_f32_e32 v94, 1.0, v94
	v_add_f32_e32 v95, 1.0, v95
	v_rcp_f32_e32 v94, v94
	v_rcp_f32_e32 v95, v95
	v_pk_mul_f32 v[84:85], v[84:85], v[92:93]
	v_pk_mul_f32 v[80:81], v[80:81], v[98:99] op_sel_hi:[1,0]
	v_pk_mul_f32 v[82:83], v[82:83], v[98:99] op_sel_hi:[1,0]
	v_pk_mul_f32 v[84:85], v[80:81], v[84:85]
	v_pk_mul_f32 v[80:81], v[86:87], v[94:95]
	s_nop 0
	v_pk_mul_f32 v[86:87], v[82:83], v[80:81]
	v_cvt_pk_bf16_f32 v82, v84, v85
	v_mov_b64_e32 v[84:85], s[8:9]
	v_mad_u64_u32 v[84:85], s[0:1], v96, s90, v[84:85]
	v_cvt_pk_bf16_f32 v83, v86, v87
	v_mov_b32_e32 v86, v85
	v_mad_u64_u32 v[86:87], s[0:1], v97, s90, v[86:87]
	v_mov_b32_e32 v85, v86
	v_cvt_pk_bf16_f32 v80, v88, v89
	v_cvt_pk_bf16_f32 v81, v90, v91
	v_lshl_add_u64 v[84:85], v[136:137], 1, v[84:85]
	global_store_dwordx4 v[84:85], v[80:83], off
	s_mov_b64 s[0:1], -1
	s_nop 0
	v_or_b32_e32 v80, 48, v138
	v_ashrrev_i32_e32 v81, 31, v80
	s_cbranch_vccnz .LBB0_1428
	v_lshl_add_u64 v[82:83], v[138:139], 2, v[130:131]
	v_add_co_u32_e32 v84, vcc, 0x10000, v82
	s_mov_b64 s[0:1], 0
	s_nop 0
	v_addc_co_u32_e32 v85, vcc, 0, v83, vcc
	v_add_co_u32_e32 v86, vcc, 0x20000, v82
	s_nop 1
	v_addc_co_u32_e32 v87, vcc, 0, v83, vcc
	v_add_co_u32_e32 v88, vcc, 0x30000, v82
	s_nop 1
	v_addc_co_u32_e32 v89, vcc, 0, v83, vcc
	v_add_co_u32_e32 v90, vcc, 0x40000, v82
	s_nop 1
	v_addc_co_u32_e32 v91, vcc, 0, v83, vcc
	v_add_co_u32_e32 v92, vcc, 0x50000, v82
	s_nop 1
	v_addc_co_u32_e32 v93, vcc, 0, v83, vcc
	v_add_co_u32_e32 v94, vcc, 0x60000, v82
	s_nop 1
	v_addc_co_u32_e32 v95, vcc, 0, v83, vcc
	v_add_co_u32_e32 v96, vcc, 0x70000, v82
	s_nop 1
	v_addc_co_u32_e32 v97, vcc, 0, v83, vcc
	v_xor_b32_e32 v90, 16, v170
	v_cmp_lt_i32_e32 vcc, v90, v171
	s_waitcnt vmcnt(27)
	v_mov_b32_e32 v82, v252
	v_mov_b32_e32 v83, v253
	v_mov_b32_e32 v84, v188
	v_mov_b32_e32 v85, v189
	v_mov_b32_e32 v86, v190
	v_mov_b32_e32 v87, v191
	v_mov_b32_e32 v88, v192
	v_mov_b32_e32 v89, v193
	global_load_dword v252, v[194:195], off offset:704
	global_load_dword v253, v[196:197], off offset:704
	global_load_dword v188, v[198:199], off offset:704
	global_load_dword v189, v[200:201], off offset:704
	global_load_dword v190, v[202:203], off offset:704
	global_load_dword v191, v[204:205], off offset:704
	global_load_dword v192, v[206:207], off offset:704
	global_load_dword v193, v[208:209], off offset:704
	v_add_f32_e32 v82, 0, v82
	v_add_f32_e32 v82, v82, v83
	v_add_f32_e32 v82, v82, v84
	v_add_f32_e32 v82, v82, v85
	v_add_f32_e32 v82, v82, v86
	v_add_f32_e32 v82, v82, v87
	v_cndmask_b32_e32 v90, v170, v90, vcc
	v_add_f32_e32 v82, v82, v88
	v_lshlrev_b32_e32 v90, 2, v90
	v_add_f32_e32 v82, v82, v89
	ds_bpermute_b32 v83, v90, v82
	v_xor_b32_e32 v84, 32, v170
	v_cmp_lt_i32_e32 vcc, v84, v171
	s_waitcnt lgkmcnt(0)
	v_add_f32_e32 v82, v82, v83
	v_cndmask_b32_e32 v84, v170, v84, vcc
	v_lshlrev_b32_e32 v84, 2, v84
	ds_bpermute_b32 v83, v84, v82
	s_waitcnt lgkmcnt(0)
	v_add_f32_e32 v82, v82, v83
	v_fmamk_f32 v82, v82, 0x3a000000, v167
	v_mul_f32_e32 v83, 0x4b800000, v82
	v_cmp_gt_f32_e32 vcc, s33, v82
	s_nop 1
	v_cndmask_b32_e32 v82, v82, v83, vcc
	v_rsq_f32_e32 v82, v82
	s_nop 0
	v_mul_f32_e32 v83, 0x45800000, v82
	v_cndmask_b32_e32 v82, v82, v83, vcc

; __device__ __forceinline__ unsigned pk2(float lo, float hi) { return pg8::cvt_pk_bf16(lo, hi); }
; __device__ __forceinline__ float sigmoidf_(float x) { return __builtin_amdgcn_rcpf(1.f + fexp(-x)); }
;     __device__ __forceinline__ float rs(int r, int fq) const { return (r >> 8) == tab_pm ? tab[r & 255] : row_rstd(rowsq, r, fq); }
;     __device__ __forceinline__ float rs(int r, int fq) const { return (r >> 8) == tab_pm ? tab[r & 255] : row_rstd(rowsq, r, fq); }
; __device__ __forceinline__ float row_rstd(const float* part, int r, int fq) {
;     float s = 0.f;
; #pragma unroll
;     for (int k = 0; k < 8; ++k) s += part[(size_t)(fq * 8 + k) * MTOK + r];
;     s += __shfl_xor(s, 16); s += __shfl_xor(s, 32);
;     return rsqrtf(s * (1.f / DM) + EPS);
; }
;     __device__ __forceinline__ void operator()(const f32x4 (&acc)[2][2][4][2], const pg8::Unit& u, int wr, int wc, int fr, int fq) const {
;     ...
;                 const int r = row0 + ai * 128 + m * 16;
;                 const float rstd = rs(r, fq);
;                 float o[2][4];
; #pragma unroll
;                 for (int bj = 0; bj < 2; ++bj) {
;                     const f32x4 gv = acc[ai][bj][m][0] * rstd, uv = acc[ai][bj][m][1] * rstd;
; #pragma unroll
;                     for (int i = 0; i < 4; ++i) o[bj][i] = gv[i] * sigmoidf_(gv[i]) * uv[i];
;                 }
;                 const int j0 = u.pn * 128 + wc * 32 + 8 * fq;
;                 u32x4 w; w.x = pk2(o[0][0], o[0][1]); w.y = pk2(o[0][2], o[0][3]); w.z = pk2(o[1][0], o[1][1]); w.w = pk2(o[1][2], o[1][3]);
;                 *(u32x4*)(HID + (size_t)r * DFF + j0) = w;
.LBB0_1430:
	s_waitcnt lgkmcnt(0)
	v_pk_mul_f32 v[76:77], v[76:77], v[82:83] op_sel_hi:[1,0]
	s_nop 0
	v_mul_f32_e32 v83, 0xbfb8aa3b, v76
	v_exp_f32_e32 v83, v83
	v_mul_f32_e32 v84, 0xbfb8aa3b, v77
	v_exp_f32_e32 v84, v84
	v_add_f32_e32 v83, 1.0, v83
	v_pk_mul_f32 v[78:79], v[78:79], v[82:83] op_sel_hi:[1,0]
	v_add_f32_e32 v85, 1.0, v84
	v_rcp_f32_e32 v84, v83
	v_mul_f32_e32 v83, 0xbfb8aa3b, v78
	v_exp_f32_e32 v83, v83
	v_mul_f32_e32 v86, 0xbfb8aa3b, v79
	v_exp_f32_e32 v87, v86
	v_rcp_f32_e32 v85, v85
	v_add_f32_e32 v83, 1.0, v83
	v_rcp_f32_e32 v86, v83
	v_add_f32_e32 v83, 1.0, v87
	v_rcp_f32_e32 v87, v83
	v_pk_mul_f32 v[76:77], v[76:77], v[84:85]
	v_pk_mul_f32 v[72:73], v[72:73], v[82:83] op_sel_hi:[1,0]
	v_pk_mul_f32 v[68:69], v[68:69], v[82:83] op_sel_hi:[1,0]
	v_pk_mul_f32 v[72:73], v[72:73], v[76:77]
	v_pk_mul_f32 v[76:77], v[78:79], v[86:87]
	v_mul_f32_e32 v78, 0xbfb8aa3b, v68
	v_mul_f32_e32 v79, 0xbfb8aa3b, v69
	v_exp_f32_e32 v78, v78
	v_exp_f32_e32 v79, v79
	v_pk_mul_f32 v[74:75], v[74:75], v[82:83] op_sel_hi:[1,0]
	v_pk_mul_f32 v[70:71], v[70:71], v[82:83] op_sel_hi:[1,0]
	v_pk_mul_f32 v[74:75], v[74:75], v[76:77]
	v_add_f32_e32 v76, 1.0, v78
	v_add_f32_e32 v77, 1.0, v79
	v_mul_f32_e32 v78, 0xbfb8aa3b, v70
	v_mul_f32_e32 v79, 0xbfb8aa3b, v71
	v_exp_f32_e32 v78, v78
	v_exp_f32_e32 v79, v79
	v_rcp_f32_e32 v76, v76
	v_rcp_f32_e32 v77, v77
	v_add_f32_e32 v78, 1.0, v78
	v_add_f32_e32 v79, 1.0, v79
	v_rcp_f32_e32 v78, v78
	v_rcp_f32_e32 v79, v79
	v_pk_mul_f32 v[68:69], v[68:69], v[76:77]
	v_pk_mul_f32 v[64:65], v[64:65], v[82:83] op_sel_hi:[1,0]
	v_pk_mul_f32 v[66:67], v[66:67], v[82:83] op_sel_hi:[1,0]
	v_pk_mul_f32 v[68:69], v[64:65], v[68:69]
	v_pk_mul_f32 v[64:65], v[70:71], v[78:79]
	s_nop 0
	v_pk_mul_f32 v[70:71], v[66:67], v[64:65]
	v_cvt_pk_bf16_f32 v66, v68, v69
	v_mov_b64_e32 v[68:69], s[8:9]
	v_mad_u64_u32 v[68:69], s[0:1], v80, s90, v[68:69]
	v_cvt_pk_bf16_f32 v67, v70, v71
	v_mov_b32_e32 v70, v69
	v_mad_u64_u32 v[70:71], s[0:1], v81, s90, v[70:71]
	v_mov_b32_e32 v69, v70
	v_cvt_pk_bf16_f32 v64, v72, v73
	v_cvt_pk_bf16_f32 v65, v74, v75
	v_lshl_add_u64 v[68:69], v[136:137], 1, v[68:69]
	global_store_dwordx4 v[68:69], v[64:67], off
	s_nop 1
	v_add_u32_e32 v64, 0x80, v138
	v_ashrrev_i32_e32 v65, 8, v64
	v_cmp_ne_u32_e64 s[4:5], s29, v65
	v_ashrrev_i32_e32 v65, 31, v64
	s_and_saveexec_b64 s[0:1], s[4:5]
	s_xor_b64 s[0:1], exec, s[0:1]
	s_cbranch_execz .LBB0_1432
	v_lshl_add_u64 v[66:67], v[138:139], 2, v[130:131]
	v_add_co_u32_e32 v68, vcc, 0x10000, v66
	s_nop 1
	v_addc_co_u32_e32 v69, vcc, 0, v67, vcc
	v_add_co_u32_e32 v70, vcc, 0x20000, v66
	s_nop 1
	v_addc_co_u32_e32 v71, vcc, 0, v67, vcc
	v_add_co_u32_e32 v72, vcc, 0x30000, v66
	s_nop 1
	v_addc_co_u32_e32 v73, vcc, 0, v67, vcc
	v_add_co_u32_e32 v74, vcc, 0x40000, v66
	s_nop 1
	v_addc_co_u32_e32 v75, vcc, 0, v67, vcc
	v_add_co_u32_e32 v76, vcc, 0x50000, v66
	s_nop 1
	v_addc_co_u32_e32 v77, vcc, 0, v67, vcc
	v_add_co_u32_e32 v78, vcc, 0x60000, v66
	s_nop 1
	v_addc_co_u32_e32 v79, vcc, 0, v67, vcc
	v_add_co_u32_e32 v80, vcc, 0x70000, v66
	s_nop 1
	v_addc_co_u32_e32 v81, vcc, 0, v67, vcc
	v_xor_b32_e32 v74, 16, v170
	v_cmp_lt_i32_e32 vcc, v74, v171
	s_waitcnt vmcnt(28)
	v_mov_b32_e32 v66, v228
	v_mov_b32_e32 v67, v229
	v_mov_b32_e32 v68, v230
	v_mov_b32_e32 v69, v231
	v_mov_b32_e32 v70, v232
	v_mov_b32_e32 v71, v233
	v_mov_b32_e32 v72, v234
	v_mov_b32_e32 v73, v235
	v_add_f32_e32 v66, 0, v66
	v_add_f32_e32 v66, v66, v67
	v_add_f32_e32 v66, v66, v68
	v_add_f32_e32 v66, v66, v69
	v_add_f32_e32 v66, v66, v70
	v_add_f32_e32 v66, v66, v71
	v_cndmask_b32_e32 v74, v170, v74, vcc
	v_add_f32_e32 v66, v66, v72
	v_lshlrev_b32_e32 v74, 2, v74
	v_add_f32_e32 v66, v66, v73
	ds_bpermute_b32 v67, v74, v66
	v_xor_b32_e32 v68, 32, v170
	v_cmp_lt_i32_e32 vcc, v68, v171
	s_waitcnt lgkmcnt(0)
	v_add_f32_e32 v66, v66, v67
	v_cndmask_b32_e32 v68, v170, v68, vcc
	v_lshlrev_b32_e32 v68, 2, v68
	ds_bpermute_b32 v67, v68, v66
	s_waitcnt lgkmcnt(0)
	v_add_f32_e32 v66, v66, v67
	v_fmamk_f32 v66, v66, 0x3a000000, v167
	v_mul_f32_e32 v67, 0x4b800000, v66
	v_cmp_gt_f32_e32 vcc, s33, v66
	s_nop 1
	v_cndmask_b32_e32 v66, v66, v67, vcc
	v_rsq_f32_e32 v66, v66
	s_nop 0
	v_mul_f32_e32 v67, 0x45800000, v66
	v_cndmask_b32_e32 v66, v66, v67, vcc
; __device__ __forceinline__ unsigned pk2(float lo, float hi) { return pg8::cvt_pk_bf16(lo, hi); }
; __device__ __forceinline__ float sigmoidf_(float x) { return __builtin_amdgcn_rcpf(1.f + fexp(-x)); }
;     __device__ __forceinline__ float rs(int r, int fq) const { return (r >> 8) == tab_pm ? tab[r & 255] : row_rstd(rowsq, r, fq); }
;     __device__ __forceinline__ float rs(int r, int fq) const { return (r >> 8) == tab_pm ? tab[r & 255] : row_rstd(rowsq, r, fq); }
; __device__ __forceinline__ float row_rstd(const float* part, int r, int fq) {
;     float s = 0.f;
; #pragma unroll
;     for (int k = 0; k < 8; ++k) s += part[(size_t)(fq * 8 + k) * MTOK + r];
;     s += __shfl_xor(s, 16); s += __shfl_xor(s, 32);
;     return rsqrtf(s * (1.f / DM) + EPS);
; }
;     __device__ __forceinline__ void operator()(const f32x4 (&acc)[2][2][4][2], const pg8::Unit& u, int wr, int wc, int fr, int fq) const {
;     ...
;                 const int r = row0 + ai * 128 + m * 16;
;                 const float rstd = rs(r, fq);
;                 float o[2][4];
; #pragma unroll
;                 for (int bj = 0; bj < 2; ++bj) {
;                     const f32x4 gv = acc[ai][bj][m][0] * rstd, uv = acc[ai][bj][m][1] * rstd;
; #pragma unroll
;                     for (int i = 0; i < 4; ++i) o[bj][i] = gv[i] * sigmoidf_(gv[i]) * uv[i];
;                 }
;                 const int j0 = u.pn * 128 + wc * 32 + 8 * fq;
;                 u32x4 w; w.x = pk2(o[0][0], o[0][1]); w.y = pk2(o[0][2], o[0][3]); w.z = pk2(o[1][0], o[1][1]); w.w = pk2(o[1][2], o[1][3]);
;                 *(u32x4*)(HID + (size_t)r * DFF + j0) = w;
.LBB0_1432:
	s_andn2_saveexec_b64 s[0:1], s[0:1]
	v_and_b32_e32 v66, 0xcf, v64
	v_lshl_add_u32 v66, v66, 2, 0
	v_add_u32_e32 v66, 0x20000, v66
	ds_read_b32 v66, v66
	s_or_b64 exec, exec, s[0:1]
	s_waitcnt lgkmcnt(0)
	v_pk_mul_f32 v[60:61], v[60:61], v[66:67] op_sel_hi:[1,0]
	s_nop 0
	v_mul_f32_e32 v67, 0xbfb8aa3b, v60
	v_exp_f32_e32 v67, v67
	v_mul_f32_e32 v68, 0xbfb8aa3b, v61
	v_exp_f32_e32 v68, v68
	v_add_f32_e32 v67, 1.0, v67
	v_pk_mul_f32 v[62:63], v[62:63], v[66:67] op_sel_hi:[1,0]
	v_add_f32_e32 v69, 1.0, v68
	v_rcp_f32_e32 v68, v67
	v_mul_f32_e32 v67, 0xbfb8aa3b, v62
	v_exp_f32_e32 v67, v67
	v_mul_f32_e32 v70, 0xbfb8aa3b, v63
	v_exp_f32_e32 v71, v70
	v_rcp_f32_e32 v69, v69
	v_add_f32_e32 v67, 1.0, v67
	v_rcp_f32_e32 v70, v67
	v_add_f32_e32 v67, 1.0, v71
	v_rcp_f32_e32 v71, v67
	v_pk_mul_f32 v[60:61], v[60:61], v[68:69]
	v_pk_mul_f32 v[56:57], v[56:57], v[66:67] op_sel_hi:[1,0]
	v_pk_mul_f32 v[52:53], v[52:53], v[66:67] op_sel_hi:[1,0]
	v_pk_mul_f32 v[56:57], v[56:57], v[60:61]
	v_pk_mul_f32 v[60:61], v[62:63], v[70:71]
	v_mul_f32_e32 v62, 0xbfb8aa3b, v52
	v_mul_f32_e32 v63, 0xbfb8aa3b, v53
	v_exp_f32_e32 v62, v62
	v_exp_f32_e32 v63, v63
	v_pk_mul_f32 v[58:59], v[58:59], v[66:67] op_sel_hi:[1,0]
	v_pk_mul_f32 v[54:55], v[54:55], v[66:67] op_sel_hi:[1,0]
	v_pk_mul_f32 v[58:59], v[58:59], v[60:61]
	v_add_f32_e32 v60, 1.0, v62
	v_add_f32_e32 v61, 1.0, v63
	v_mul_f32_e32 v62, 0xbfb8aa3b, v54
	v_mul_f32_e32 v63, 0xbfb8aa3b, v55
	v_exp_f32_e32 v62, v62
	v_exp_f32_e32 v63, v63
	v_rcp_f32_e32 v60, v60
	v_rcp_f32_e32 v61, v61
	v_add_f32_e32 v62, 1.0, v62
	v_add_f32_e32 v63, 1.0, v63
	v_rcp_f32_e32 v62, v62
	v_rcp_f32_e32 v63, v63
	v_pk_mul_f32 v[52:53], v[52:53], v[60:61]
	v_pk_mul_f32 v[48:49], v[48:49], v[66:67] op_sel_hi:[1,0]
	v_pk_mul_f32 v[50:51], v[50:51], v[66:67] op_sel_hi:[1,0]
	v_pk_mul_f32 v[52:53], v[48:49], v[52:53]
	v_pk_mul_f32 v[48:49], v[54:55], v[62:63]
	s_nop 0
	v_pk_mul_f32 v[54:55], v[50:51], v[48:49]
	v_cvt_pk_bf16_f32 v50, v52, v53
	v_mov_b64_e32 v[52:53], s[8:9]
	v_mad_u64_u32 v[52:53], s[0:1], v64, s90, v[52:53]
	v_cvt_pk_bf16_f32 v51, v54, v55
	v_mov_b32_e32 v54, v53
	v_mad_u64_u32 v[54:55], s[0:1], v65, s90, v[54:55]
	v_mov_b32_e32 v53, v54
	v_cvt_pk_bf16_f32 v48, v56, v57
	v_cvt_pk_bf16_f32 v49, v58, v59
	v_lshl_add_u64 v[52:53], v[136:137], 1, v[52:53]
	global_store_dwordx4 v[52:53], v[48:51], off
	s_nop 1
	v_add_u32_e32 v48, 0x90, v138
	v_ashrrev_i32_e32 v49, 31, v48
	s_and_saveexec_b64 s[0:1], s[4:5]
	s_xor_b64 s[0:1], exec, s[0:1]
	s_cbranch_execz .LBB0_1436
	v_lshl_add_u64 v[50:51], v[138:139], 2, v[130:131]
	v_add_co_u32_e32 v52, vcc, 0x10000, v50
	s_nop 1
	v_addc_co_u32_e32 v53, vcc, 0, v51, vcc
	v_add_co_u32_e32 v54, vcc, 0x20000, v50
	s_nop 1
	v_addc_co_u32_e32 v55, vcc, 0, v51, vcc
	v_add_co_u32_e32 v56, vcc, 0x30000, v50
	s_nop 1
	v_addc_co_u32_e32 v57, vcc, 0, v51, vcc
	v_add_co_u32_e32 v58, vcc, 0x40000, v50
	s_nop 1
	v_addc_co_u32_e32 v59, vcc, 0, v51, vcc
	v_add_co_u32_e32 v60, vcc, 0x50000, v50
	s_nop 1
	v_addc_co_u32_e32 v61, vcc, 0, v51, vcc
	v_add_co_u32_e32 v62, vcc, 0x60000, v50
	s_nop 1
	v_addc_co_u32_e32 v63, vcc, 0, v51, vcc
	v_add_co_u32_e32 v64, vcc, 0x70000, v50
	s_nop 1
	v_addc_co_u32_e32 v65, vcc, 0, v51, vcc
	v_xor_b32_e32 v58, 16, v170
	v_cmp_lt_i32_e32 vcc, v58, v171
	s_waitcnt vmcnt(21)
	v_mov_b32_e32 v50, v236
	v_mov_b32_e32 v51, v237
	v_mov_b32_e32 v52, v238
	v_mov_b32_e32 v53, v239
	v_mov_b32_e32 v54, v240
	v_mov_b32_e32 v55, v241
	v_mov_b32_e32 v56, v242
	v_mov_b32_e32 v57, v243
	v_add_f32_e32 v50, 0, v50
	v_add_f32_e32 v50, v50, v51
	v_add_f32_e32 v50, v50, v52
	v_add_f32_e32 v50, v50, v53
	v_add_f32_e32 v50, v50, v54
	v_add_f32_e32 v50, v50, v55
	v_cndmask_b32_e32 v58, v170, v58, vcc
	v_add_f32_e32 v50, v50, v56
	v_lshlrev_b32_e32 v58, 2, v58
	v_add_f32_e32 v50, v50, v57
	ds_bpermute_b32 v51, v58, v50
	v_xor_b32_e32 v52, 32, v170
	v_cmp_lt_i32_e32 vcc, v52, v171
	s_waitcnt lgkmcnt(0)
	v_add_f32_e32 v50, v50, v51
	v_cndmask_b32_e32 v52, v170, v52, vcc
	v_lshlrev_b32_e32 v52, 2, v52
	ds_bpermute_b32 v51, v52, v50
	s_waitcnt lgkmcnt(0)
	v_add_f32_e32 v50, v50, v51
	v_fmamk_f32 v50, v50, 0x3a000000, v167
	v_mul_f32_e32 v51, 0x4b800000, v50
	v_cmp_gt_f32_e32 vcc, s33, v50
	s_nop 1
	v_cndmask_b32_e32 v50, v50, v51, vcc
	v_rsq_f32_e32 v50, v50
	s_nop 0
	v_mul_f32_e32 v51, 0x45800000, v50
	v_cndmask_b32_e32 v50, v50, v51, vcc
; __device__ __forceinline__ unsigned pk2(float lo, float hi) { return pg8::cvt_pk_bf16(lo, hi); }
; __device__ __forceinline__ float sigmoidf_(float x) { return __builtin_amdgcn_rcpf(1.f + fexp(-x)); }
;     __device__ __forceinline__ float rs(int r, int fq) const { return (r >> 8) == tab_pm ? tab[r & 255] : row_rstd(rowsq, r, fq); }
;     __device__ __forceinline__ float rs(int r, int fq) const { return (r >> 8) == tab_pm ? tab[r & 255] : row_rstd(rowsq, r, fq); }
; __device__ __forceinline__ float row_rstd(const float* part, int r, int fq) {
;     float s = 0.f;
; #pragma unroll
;     for (int k = 0; k < 8; ++k) s += part[(size_t)(fq * 8 + k) * MTOK + r];
;     s += __shfl_xor(s, 16); s += __shfl_xor(s, 32);
;     return rsqrtf(s * (1.f / DM) + EPS);
; }
;     __device__ __forceinline__ void operator()(const f32x4 (&acc)[2][2][4][2], const pg8::Unit& u, int wr, int wc, int fr, int fq) const {
;     ...
;                 const int r = row0 + ai * 128 + m * 16;
;                 const float rstd = rs(r, fq);
;                 float o[2][4];
; #pragma unroll
;                 for (int bj = 0; bj < 2; ++bj) {
;                     const f32x4 gv = acc[ai][bj][m][0] * rstd, uv = acc[ai][bj][m][1] * rstd;
; #pragma unroll
;                     for (int i = 0; i < 4; ++i) o[bj][i] = gv[i] * sigmoidf_(gv[i]) * uv[i];
;                 }
;                 const int j0 = u.pn * 128 + wc * 32 + 8 * fq;
;                 u32x4 w; w.x = pk2(o[0][0], o[0][1]); w.y = pk2(o[0][2], o[0][3]); w.z = pk2(o[1][0], o[1][1]); w.w = pk2(o[1][2], o[1][3]);
;                 *(u32x4*)(HID + (size_t)r * DFF + j0) = w;
.LBB0_1436:
	s_andn2_saveexec_b64 s[0:1], s[0:1]
	v_and_b32_e32 v50, 0xdf, v48
	v_lshl_add_u32 v50, v50, 2, 0
	v_add_u32_e32 v50, 0x20000, v50
	ds_read_b32 v50, v50
	s_or_b64 exec, exec, s[0:1]
	s_waitcnt lgkmcnt(0)
	v_pk_mul_f32 v[44:45], v[44:45], v[50:51] op_sel_hi:[1,0]
	s_nop 0
	v_mul_f32_e32 v51, 0xbfb8aa3b, v44
	v_exp_f32_e32 v51, v51
	v_mul_f32_e32 v52, 0xbfb8aa3b, v45
	v_exp_f32_e32 v52, v52
	v_add_f32_e32 v51, 1.0, v51
	v_pk_mul_f32 v[46:47], v[46:47], v[50:51] op_sel_hi:[1,0]
	v_add_f32_e32 v53, 1.0, v52
	v_rcp_f32_e32 v52, v51
	v_mul_f32_e32 v51, 0xbfb8aa3b, v46
	v_exp_f32_e32 v51, v51
	v_mul_f32_e32 v54, 0xbfb8aa3b, v47
	v_exp_f32_e32 v55, v54
	v_rcp_f32_e32 v53, v53
	v_add_f32_e32 v51, 1.0, v51
	v_rcp_f32_e32 v54, v51
	v_add_f32_e32 v51, 1.0, v55
	v_rcp_f32_e32 v55, v51
	v_pk_mul_f32 v[44:45], v[44:45], v[52:53]
	v_pk_mul_f32 v[40:41], v[40:41], v[50:51] op_sel_hi:[1,0]
	v_pk_mul_f32 v[36:37], v[36:37], v[50:51] op_sel_hi:[1,0]
	v_pk_mul_f32 v[40:41], v[40:41], v[44:45]
	v_pk_mul_f32 v[44:45], v[46:47], v[54:55]
	v_mul_f32_e32 v46, 0xbfb8aa3b, v36
	v_mul_f32_e32 v47, 0xbfb8aa3b, v37
	v_exp_f32_e32 v46, v46
	v_exp_f32_e32 v47, v47
	v_pk_mul_f32 v[42:43], v[42:43], v[50:51] op_sel_hi:[1,0]
	v_pk_mul_f32 v[38:39], v[38:39], v[50:51] op_sel_hi:[1,0]
	v_pk_mul_f32 v[42:43], v[42:43], v[44:45]
	v_add_f32_e32 v44, 1.0, v46
	v_add_f32_e32 v45, 1.0, v47
	v_mul_f32_e32 v46, 0xbfb8aa3b, v38
	v_mul_f32_e32 v47, 0xbfb8aa3b, v39
	v_exp_f32_e32 v46, v46
	v_exp_f32_e32 v47, v47
	v_rcp_f32_e32 v44, v44
	v_rcp_f32_e32 v45, v45
	v_add_f32_e32 v46, 1.0, v46
	v_add_f32_e32 v47, 1.0, v47
	v_rcp_f32_e32 v46, v46
	v_rcp_f32_e32 v47, v47
	v_pk_mul_f32 v[36:37], v[36:37], v[44:45]
	v_pk_mul_f32 v[32:33], v[32:33], v[50:51] op_sel_hi:[1,0]
	v_pk_mul_f32 v[34:35], v[34:35], v[50:51] op_sel_hi:[1,0]
	v_pk_mul_f32 v[36:37], v[32:33], v[36:37]
	v_pk_mul_f32 v[32:33], v[38:39], v[46:47]
	s_nop 0
	v_pk_mul_f32 v[38:39], v[34:35], v[32:33]
	v_cvt_pk_bf16_f32 v34, v36, v37
	v_mov_b64_e32 v[36:37], s[8:9]
	v_mad_u64_u32 v[36:37], s[0:1], v48, s90, v[36:37]
	v_cvt_pk_bf16_f32 v35, v38, v39
	v_mov_b32_e32 v38, v37
	v_mad_u64_u32 v[38:39], s[0:1], v49, s90, v[38:39]
	v_mov_b32_e32 v37, v38
	v_cvt_pk_bf16_f32 v32, v40, v41
	v_cvt_pk_bf16_f32 v33, v42, v43
	v_lshl_add_u64 v[36:37], v[136:137], 1, v[36:37]
	global_store_dwordx4 v[36:37], v[32:35], off
	s_nop 1
	v_add_u32_e32 v32, 0xa0, v138
	v_ashrrev_i32_e32 v33, 31, v32
	s_and_saveexec_b64 s[0:1], s[4:5]
	s_xor_b64 s[0:1], exec, s[0:1]
	s_cbranch_execz .LBB0_1440
	v_lshl_add_u64 v[34:35], v[138:139], 2, v[130:131]
	v_add_co_u32_e32 v36, vcc, 0x10000, v34
	s_nop 1
	v_addc_co_u32_e32 v37, vcc, 0, v35, vcc
	v_add_co_u32_e32 v38, vcc, 0x20000, v34
	s_nop 1
	v_addc_co_u32_e32 v39, vcc, 0, v35, vcc
	v_add_co_u32_e32 v40, vcc, 0x30000, v34
	s_nop 1
	v_addc_co_u32_e32 v41, vcc, 0, v35, vcc
	v_add_co_u32_e32 v42, vcc, 0x40000, v34
	s_nop 1
	v_addc_co_u32_e32 v43, vcc, 0, v35, vcc
	v_add_co_u32_e32 v44, vcc, 0x50000, v34
	s_nop 1
	v_addc_co_u32_e32 v45, vcc, 0, v35, vcc
	v_add_co_u32_e32 v46, vcc, 0x60000, v34
	s_nop 1
	v_addc_co_u32_e32 v47, vcc, 0, v35, vcc
	v_add_co_u32_e32 v48, vcc, 0x70000, v34
	s_nop 1
	v_addc_co_u32_e32 v49, vcc, 0, v35, vcc
	v_xor_b32_e32 v42, 16, v170
	v_cmp_lt_i32_e32 vcc, v42, v171
	s_waitcnt vmcnt(13)
	v_mov_b32_e32 v34, v244
	v_mov_b32_e32 v35, v245
	v_mov_b32_e32 v36, v246
	v_mov_b32_e32 v37, v247
	v_mov_b32_e32 v38, v248
	v_mov_b32_e32 v39, v249
	v_mov_b32_e32 v40, v250
	v_mov_b32_e32 v41, v251
	v_add_f32_e32 v34, 0, v34
	v_add_f32_e32 v34, v34, v35
	v_add_f32_e32 v34, v34, v36
	v_add_f32_e32 v34, v34, v37
	v_add_f32_e32 v34, v34, v38
	v_add_f32_e32 v34, v34, v39
	v_cndmask_b32_e32 v42, v170, v42, vcc
	v_add_f32_e32 v34, v34, v40
	v_lshlrev_b32_e32 v42, 2, v42
	v_add_f32_e32 v34, v34, v41
	ds_bpermute_b32 v35, v42, v34
	v_xor_b32_e32 v36, 32, v170
	v_cmp_lt_i32_e32 vcc, v36, v171
	s_waitcnt lgkmcnt(0)
	v_add_f32_e32 v34, v34, v35
	v_cndmask_b32_e32 v36, v170, v36, vcc
	v_lshlrev_b32_e32 v36, 2, v36
	ds_bpermute_b32 v35, v36, v34
	s_waitcnt lgkmcnt(0)
	v_add_f32_e32 v34, v34, v35
	v_fmamk_f32 v34, v34, 0x3a000000, v167
	v_mul_f32_e32 v35, 0x4b800000, v34
	v_cmp_gt_f32_e32 vcc, s33, v34
	s_nop 1
	v_cndmask_b32_e32 v34, v34, v35, vcc
	v_rsq_f32_e32 v34, v34
	s_nop 0
	v_mul_f32_e32 v35, 0x45800000, v34
	v_cndmask_b32_e32 v34, v34, v35, vcc
; __device__ __forceinline__ unsigned pk2(float lo, float hi) { return pg8::cvt_pk_bf16(lo, hi); }
; __device__ __forceinline__ float sigmoidf_(float x) { return __builtin_amdgcn_rcpf(1.f + fexp(-x)); }
;     __device__ __forceinline__ float rs(int r, int fq) const { return (r >> 8) == tab_pm ? tab[r & 255] : row_rstd(rowsq, r, fq); }
;     __device__ __forceinline__ float rs(int r, int fq) const { return (r >> 8) == tab_pm ? tab[r & 255] : row_rstd(rowsq, r, fq); }
; __device__ __forceinline__ float row_rstd(const float* part, int r, int fq) {
;     float s = 0.f;
; #pragma unroll
;     for (int k = 0; k < 8; ++k) s += part[(size_t)(fq * 8 + k) * MTOK + r];
;     s += __shfl_xor(s, 16); s += __shfl_xor(s, 32);
;     return rsqrtf(s * (1.f / DM) + EPS);
; }
;     __device__ __forceinline__ void operator()(const f32x4 (&acc)[2][2][4][2], const pg8::Unit& u, int wr, int wc, int fr, int fq) const {
;     ...
;                 const int r = row0 + ai * 128 + m * 16;
;                 const float rstd = rs(r, fq);
;                 float o[2][4];
; #pragma unroll
;                 for (int bj = 0; bj < 2; ++bj) {
;                     const f32x4 gv = acc[ai][bj][m][0] * rstd, uv = acc[ai][bj][m][1] * rstd;
; #pragma unroll
;                     for (int i = 0; i < 4; ++i) o[bj][i] = gv[i] * sigmoidf_(gv[i]) * uv[i];
;                 }
;                 const int j0 = u.pn * 128 + wc * 32 + 8 * fq;
;                 u32x4 w; w.x = pk2(o[0][0], o[0][1]); w.y = pk2(o[0][2], o[0][3]); w.z = pk2(o[1][0], o[1][1]); w.w = pk2(o[1][2], o[1][3]);
;                 *(u32x4*)(HID + (size_t)r * DFF + j0) = w;
.LBB0_1440:
	s_andn2_saveexec_b64 s[0:1], s[0:1]
	v_and_b32_e32 v34, 0xef, v32
	v_lshl_add_u32 v34, v34, 2, 0
	v_add_u32_e32 v34, 0x20000, v34
	ds_read_b32 v34, v34
	s_or_b64 exec, exec, s[0:1]
	s_waitcnt lgkmcnt(0)
	v_pk_mul_f32 v[28:29], v[28:29], v[34:35] op_sel_hi:[1,0]
	s_nop 0
	v_mul_f32_e32 v35, 0xbfb8aa3b, v28
	v_exp_f32_e32 v35, v35
	v_mul_f32_e32 v36, 0xbfb8aa3b, v29
	v_exp_f32_e32 v36, v36
	v_add_f32_e32 v35, 1.0, v35
	v_pk_mul_f32 v[30:31], v[30:31], v[34:35] op_sel_hi:[1,0]
	v_add_f32_e32 v37, 1.0, v36
	v_rcp_f32_e32 v36, v35
	v_mul_f32_e32 v35, 0xbfb8aa3b, v30
	v_exp_f32_e32 v35, v35
	v_mul_f32_e32 v38, 0xbfb8aa3b, v31
	v_exp_f32_e32 v39, v38
	v_rcp_f32_e32 v37, v37
	v_add_f32_e32 v35, 1.0, v35
	v_rcp_f32_e32 v38, v35
	v_add_f32_e32 v35, 1.0, v39
	v_rcp_f32_e32 v39, v35
	v_pk_mul_f32 v[28:29], v[28:29], v[36:37]
	v_pk_mul_f32 v[24:25], v[24:25], v[34:35] op_sel_hi:[1,0]
	v_pk_mul_f32 v[20:21], v[20:21], v[34:35] op_sel_hi:[1,0]
	v_pk_mul_f32 v[24:25], v[24:25], v[28:29]
	v_pk_mul_f32 v[28:29], v[30:31], v[38:39]
	v_mul_f32_e32 v30, 0xbfb8aa3b, v20
	v_mul_f32_e32 v31, 0xbfb8aa3b, v21
	v_exp_f32_e32 v30, v30
	v_exp_f32_e32 v31, v31
	v_pk_mul_f32 v[26:27], v[26:27], v[34:35] op_sel_hi:[1,0]
	v_pk_mul_f32 v[22:23], v[22:23], v[34:35] op_sel_hi:[1,0]
	v_pk_mul_f32 v[26:27], v[26:27], v[28:29]
	v_add_f32_e32 v28, 1.0, v30
	v_add_f32_e32 v29, 1.0, v31
	v_mul_f32_e32 v30, 0xbfb8aa3b, v22
	v_mul_f32_e32 v31, 0xbfb8aa3b, v23
	v_exp_f32_e32 v30, v30
	v_exp_f32_e32 v31, v31
	v_rcp_f32_e32 v28, v28
	v_rcp_f32_e32 v29, v29
	v_add_f32_e32 v30, 1.0, v30
	v_add_f32_e32 v31, 1.0, v31
	v_rcp_f32_e32 v30, v30
	v_rcp_f32_e32 v31, v31
	v_pk_mul_f32 v[20:21], v[20:21], v[28:29]
	v_pk_mul_f32 v[16:17], v[16:17], v[34:35] op_sel_hi:[1,0]
	v_pk_mul_f32 v[18:19], v[18:19], v[34:35] op_sel_hi:[1,0]
	v_pk_mul_f32 v[20:21], v[16:17], v[20:21]
	v_pk_mul_f32 v[16:17], v[22:23], v[30:31]
	s_nop 0
	v_pk_mul_f32 v[22:23], v[18:19], v[16:17]
	v_cvt_pk_bf16_f32 v18, v20, v21
	v_mov_b64_e32 v[20:21], s[8:9]
	v_mad_u64_u32 v[20:21], s[0:1], v32, s90, v[20:21]
	v_cvt_pk_bf16_f32 v19, v22, v23
	v_mov_b32_e32 v22, v21
	v_mad_u64_u32 v[22:23], s[0:1], v33, s90, v[22:23]
	v_mov_b32_e32 v21, v22
	v_cvt_pk_bf16_f32 v16, v24, v25
	v_cvt_pk_bf16_f32 v17, v26, v27
	v_lshl_add_u64 v[20:21], v[136:137], 1, v[20:21]
	global_store_dwordx4 v[20:21], v[16:19], off
	s_nop 1
	v_add_u32_e32 v16, 0xb0, v138
	v_ashrrev_i32_e32 v17, 31, v16
	s_and_saveexec_b64 s[0:1], s[4:5]
	s_xor_b64 s[0:1], exec, s[0:1]
	s_cbranch_execz .LBB0_1444
	v_lshl_add_u64 v[18:19], v[138:139], 2, v[130:131]
	v_add_co_u32_e32 v20, vcc, 0x10000, v18
	s_nop 1
	v_addc_co_u32_e32 v21, vcc, 0, v19, vcc
	v_add_co_u32_e32 v22, vcc, 0x20000, v18
	s_nop 1
	v_addc_co_u32_e32 v23, vcc, 0, v19, vcc
	v_add_co_u32_e32 v24, vcc, 0x30000, v18
	s_nop 1
	v_addc_co_u32_e32 v25, vcc, 0, v19, vcc
	v_add_co_u32_e32 v26, vcc, 0x40000, v18
	s_nop 1
	v_addc_co_u32_e32 v27, vcc, 0, v19, vcc
	v_add_co_u32_e32 v28, vcc, 0x50000, v18
	s_nop 1
	v_addc_co_u32_e32 v29, vcc, 0, v19, vcc
	v_add_co_u32_e32 v30, vcc, 0x60000, v18
	s_nop 1
	v_addc_co_u32_e32 v31, vcc, 0, v19, vcc
	v_add_co_u32_e32 v32, vcc, 0x70000, v18
	s_nop 1
	v_addc_co_u32_e32 v33, vcc, 0, v19, vcc
	v_xor_b32_e32 v26, 16, v170
	v_cmp_lt_i32_e32 vcc, v26, v171
	s_waitcnt vmcnt(4)
	v_mov_b32_e32 v18, v252
	v_mov_b32_e32 v19, v253
	v_mov_b32_e32 v20, v188
	v_mov_b32_e32 v21, v189
	v_mov_b32_e32 v22, v190
	v_mov_b32_e32 v23, v191
	v_mov_b32_e32 v24, v192
	v_mov_b32_e32 v25, v193
	v_add_f32_e32 v18, 0, v18
	v_add_f32_e32 v18, v18, v19
	v_add_f32_e32 v18, v18, v20
	v_add_f32_e32 v18, v18, v21
	v_add_f32_e32 v18, v18, v22
	v_add_f32_e32 v18, v18, v23
	v_cndmask_b32_e32 v26, v170, v26, vcc
	v_add_f32_e32 v18, v18, v24
	v_lshlrev_b32_e32 v26, 2, v26
	v_add_f32_e32 v18, v18, v25
	ds_bpermute_b32 v19, v26, v18
	v_xor_b32_e32 v20, 32, v170
	v_cmp_lt_i32_e32 vcc, v20, v171
	s_waitcnt lgkmcnt(0)
	v_add_f32_e32 v18, v18, v19
	v_cndmask_b32_e32 v20, v170, v20, vcc
	v_lshlrev_b32_e32 v20, 2, v20
	ds_bpermute_b32 v19, v20, v18
	s_waitcnt lgkmcnt(0)
	v_add_f32_e32 v18, v18, v19
	v_fmamk_f32 v18, v18, 0x3a000000, v167
	v_mul_f32_e32 v19, 0x4b800000, v18
	v_cmp_gt_f32_e32 vcc, s33, v18
	s_nop 1
	v_cndmask_b32_e32 v18, v18, v19, vcc
	v_rsq_f32_e32 v18, v18
	s_nop 0
	v_mul_f32_e32 v19, 0x45800000, v18
	v_cndmask_b32_e32 v18, v18, v19, vcc

; __device__ __forceinline__ CArgs* get_args() { CArgs* p = (CArgs*)__builtin_amdgcn_kernarg_segment_ptr(); asm volatile("" : "+s"(p)); return p; }
; __global__ void __launch_bounds__(512, 2) hymba_fwd(Args A_unused) {
;     ...
;             PHASE_IDS(); CArgs* Ap = get_args(); unsigned char* ws = Ap->ws;
;             pg8::Gemm g{(const bf16_t*)(ws + WS_HID), (const bf16_t*)(ws + WS_WDN) + (size_t)l * DM * DFF, MTOK, DM, DFF}; pg8::StaticOrder S; S.init(MTOK, DM, G, blk);
.LBB0_1464:
	s_or_b64 exec, exec, s[0:1]
	s_mov_b32 s0, s77
	s_barrier
	s_waitcnt vmcnt(0) lgkmcnt(0)
	v_mbcnt_lo_u32_b32 v0, -1, 0
	v_mbcnt_hi_u32_b32 v0, -1, v0
	s_mov_b32 s22, s67
	v_lshl_add_u32 v8, s0, 6, v0
	s_mov_b32 s23, s76
	s_mov_b64 s[0:1], s[68:69]
	s_load_dwordx2 s[2:3], s[0:1], 0xd8
	s_cmpk_lt_i32 s23, 0x200
	s_cselect_b64 s[0:1], -1, 0
	s_cmpk_gt_i32 s23, 0x1ff
	v_readfirstlane_b32 s6, v8
	s_cbranch_scc1 .LBB0_1470
	s_ashr_i32 s4, s23, 31
	s_lshr_b32 s4, s4, 29
	s_add_i32 s7, s23, s4
	s_and_b32 s4, s7, -8
	s_sub_i32 s8, s23, s4
	s_cmp_gt_i32 s8, -1
	s_mov_b64 s[4:5], -1
	s_cbranch_scc0 .LBB0_1467
	s_lshl_b32 s9, s8, 6
	s_mov_b64 s[4:5], 0
